# phase 11a: per-group-count dot blocks, each group's dot products start when its own rows have arrived (counted vmcnt), reductions only for the groups present
# speedup vs baseline: 1.0009x; 1.0009x over previous
; DI void phase11a(const Params& P, char* smem_all) {
;     ...
;           const char* rowp = Uq + (long)el[gi] * 1024 + l16 * 16;
; #pragma unroll
;           for (int c = 0; c < 4; ++c) u[gi][c] = *reinterpret_cast<const uint4*>(rowp + c * 256);
;           su[gi] = Us[el[gi]]; sv[gi] = Vs[el[gi]];
;         }
;       }
;       if (!pf) {
;         pf = true;
;         nE0 = Eidx[(long)tn * 128 + lane]; nE1 = Eidx[(long)tn * 128 + 64 + lane];
;         nG0 = G[(long)tn * 128 + lane]; nG1 = G[(long)tn * 128 + 64 + lane];
; #pragma unroll
;         for (int c = 0; c < 4; ++c) nx[c] = *reinterpret_cast<const uint4*>(xq + (long)tn * 1024 + (c * 16 + l16) * 16);
;         nsx = sxp[tn];
;       }
; #pragma unroll
;       for (int gi = 0; gi < 6; ++gi) {
;         if (gi < ng) {
;           int d = 0;
; #pragma unroll
;           for (int c = 0; c < 4; ++c) {
;             d = __builtin_amdgcn_sdot4((int)u[gi][c].x, (int)xr[c].x, d, false);
;             d = __builtin_amdgcn_sdot4((int)u[gi][c].y, (int)xr[c].y, d, false);
;             d = __builtin_amdgcn_sdot4((int)u[gi][c].z, (int)xr[c].z, d, false);
;             d = __builtin_amdgcn_sdot4((int)u[gi][c].w, (int)xr[c].w, d, false);
;           }
.Lp11a_issued:
	v_lshrrev_b32_e32 v175, 8, v154
	v_and_b32_e32 v175, 0xfffc, v175
	global_load_dword v156, v175, s[32:33]
	global_load_dword v153, v175, s[28:29]
	s_cmp_lg_u32 s12, 0
	s_cbranch_scc1 .Lp11a_later
	s_lshl_b32 s0, s7, 9
	s_add_u32 s8, s38, s0
	s_addc_u32 s9, s39, 0
	global_load_dword v10, v0, s[8:9]
	global_load_dword v11, v0, s[8:9] offset:256
	s_add_u32 s8, s42, s0
	s_addc_u32 s9, s43, 0
	global_load_dword v12, v0, s[8:9]
	global_load_dword v13, v0, s[8:9] offset:256
	s_lshl_b32 s0, s7, 10
	s_add_u32 s8, s62, s0
	s_addc_u32 s9, s63, 0
	global_load_dwordx4 v[32:35], v1, s[8:9]
	global_load_dwordx4 v[36:39], v1, s[8:9] offset:256
	global_load_dwordx4 v[40:43], v1, s[8:9] offset:512
	global_load_dwordx4 v[44:47], v1, s[8:9] offset:768
	s_lshl_b32 s0, s7, 2
	s_add_u32 s8, s30, s0
	s_addc_u32 s9, s31, 0
	s_load_dword s15, s[8:9], 0x0
	s_cmp_eq_u32 s13, 4
	s_cbranch_scc1 .Lp11a_d4
	s_cmp_eq_u32 s13, 5
	s_cbranch_scc1 .Lp11a_d5
	s_cmp_eq_u32 s13, 3
	s_cbranch_scc1 .Lp11a_d3
	s_cmp_eq_u32 s13, 6
	s_cbranch_scc1 .Lp11a_d6
	s_cmp_eq_u32 s13, 2
	s_cbranch_scc1 .Lp11a_d2
.Lp11a_d1:
	s_waitcnt vmcnt(10)
	v_mov_b32_e32 v176, 0
	v_dot4c_i32_i8_e32 v176, v48, v16
	v_dot4c_i32_i8_e32 v176, v49, v17
	v_dot4c_i32_i8_e32 v176, v50, v18
	v_dot4c_i32_i8_e32 v176, v51, v19
	v_dot4c_i32_i8_e32 v176, v52, v20
	v_dot4c_i32_i8_e32 v176, v53, v21
	v_dot4c_i32_i8_e32 v176, v54, v22
	v_dot4c_i32_i8_e32 v176, v55, v23
	v_dot4c_i32_i8_e32 v176, v56, v24
	v_dot4c_i32_i8_e32 v176, v57, v25
	v_dot4c_i32_i8_e32 v176, v58, v26
	v_dot4c_i32_i8_e32 v176, v59, v27
	v_dot4c_i32_i8_e32 v176, v60, v28
	v_dot4c_i32_i8_e32 v176, v61, v29
	v_dot4c_i32_i8_e32 v176, v62, v30
	v_dot4c_i32_i8_e32 v176, v63, v31
	s_nop 2
	v_add_u32_dpp v176, v176, v176 quad_perm:[1,0,3,2] row_mask:0xf bank_mask:0xf bound_ctrl:1
	s_nop 1
	v_add_u32_dpp v176, v176, v176 quad_perm:[2,3,0,1] row_mask:0xf bank_mask:0xf bound_ctrl:1
	s_nop 1
	v_add_u32_dpp v176, v176, v176 row_half_mirror row_mask:0xf bank_mask:0xf bound_ctrl:1
	s_nop 1
	v_add_u32_dpp v176, v176, v176 row_mirror row_mask:0xf bank_mask:0xf bound_ctrl:1
	s_nop 1
	v_mov_b32_e32 v152, v176
	s_waitcnt vmcnt(8)
	s_branch .Lp11a_gelu
.Lp11a_d4:
	s_waitcnt vmcnt(22)
	v_mov_b32_e32 v176, 0
	v_dot4c_i32_i8_e32 v176, v48, v16
	v_dot4c_i32_i8_e32 v176, v49, v17
	v_dot4c_i32_i8_e32 v176, v50, v18
	v_dot4c_i32_i8_e32 v176, v51, v19
	v_dot4c_i32_i8_e32 v176, v52, v20
	v_dot4c_i32_i8_e32 v176, v53, v21
	v_dot4c_i32_i8_e32 v176, v54, v22
	v_dot4c_i32_i8_e32 v176, v55, v23
	v_dot4c_i32_i8_e32 v176, v56, v24
	v_dot4c_i32_i8_e32 v176, v57, v25
	v_dot4c_i32_i8_e32 v176, v58, v26
	v_dot4c_i32_i8_e32 v176, v59, v27
	v_dot4c_i32_i8_e32 v176, v60, v28
	v_dot4c_i32_i8_e32 v176, v61, v29
	v_dot4c_i32_i8_e32 v176, v62, v30
	v_dot4c_i32_i8_e32 v176, v63, v31
	s_waitcnt vmcnt(18)
	v_mov_b32_e32 v177, 0
	v_dot4c_i32_i8_e32 v177, v64, v16
	v_dot4c_i32_i8_e32 v177, v65, v17
	v_dot4c_i32_i8_e32 v177, v66, v18
	v_dot4c_i32_i8_e32 v177, v67, v19
	v_dot4c_i32_i8_e32 v177, v68, v20
	v_dot4c_i32_i8_e32 v177, v69, v21
	v_dot4c_i32_i8_e32 v177, v70, v22
	v_dot4c_i32_i8_e32 v177, v71, v23
	v_dot4c_i32_i8_e32 v177, v72, v24
	v_dot4c_i32_i8_e32 v177, v73, v25
	v_dot4c_i32_i8_e32 v177, v74, v26
	v_dot4c_i32_i8_e32 v177, v75, v27
	v_dot4c_i32_i8_e32 v177, v76, v28
	v_dot4c_i32_i8_e32 v177, v77, v29
	v_dot4c_i32_i8_e32 v177, v78, v30
	v_dot4c_i32_i8_e32 v177, v79, v31
	s_waitcnt vmcnt(14)
	v_mov_b32_e32 v178, 0
	v_dot4c_i32_i8_e32 v178, v80, v16
	v_dot4c_i32_i8_e32 v178, v81, v17
	v_dot4c_i32_i8_e32 v178, v82, v18
	v_dot4c_i32_i8_e32 v178, v83, v19
	v_dot4c_i32_i8_e32 v178, v84, v20
	v_dot4c_i32_i8_e32 v178, v85, v21
	v_dot4c_i32_i8_e32 v178, v86, v22
	v_dot4c_i32_i8_e32 v178, v87, v23
	v_dot4c_i32_i8_e32 v178, v88, v24
	v_dot4c_i32_i8_e32 v178, v89, v25
	v_dot4c_i32_i8_e32 v178, v90, v26
	v_dot4c_i32_i8_e32 v178, v91, v27
	v_dot4c_i32_i8_e32 v178, v92, v28
	v_dot4c_i32_i8_e32 v178, v93, v29
	v_dot4c_i32_i8_e32 v178, v94, v30
	v_dot4c_i32_i8_e32 v178, v95, v31
	s_waitcnt vmcnt(10)
	v_mov_b32_e32 v179, 0
	v_dot4c_i32_i8_e32 v179, v96, v16
	v_dot4c_i32_i8_e32 v179, v97, v17
	v_dot4c_i32_i8_e32 v179, v98, v18
	v_dot4c_i32_i8_e32 v179, v99, v19
	v_dot4c_i32_i8_e32 v179, v100, v20
	v_dot4c_i32_i8_e32 v179, v101, v21
	v_dot4c_i32_i8_e32 v179, v102, v22
	v_dot4c_i32_i8_e32 v179, v103, v23
	v_dot4c_i32_i8_e32 v179, v104, v24
	v_dot4c_i32_i8_e32 v179, v105, v25
	v_dot4c_i32_i8_e32 v179, v106, v26
	v_dot4c_i32_i8_e32 v179, v107, v27
	v_dot4c_i32_i8_e32 v179, v108, v28
	v_dot4c_i32_i8_e32 v179, v109, v29
	v_dot4c_i32_i8_e32 v179, v110, v30
	v_dot4c_i32_i8_e32 v179, v111, v31
	s_nop 2
	v_add_u32_dpp v176, v176, v176 quad_perm:[1,0,3,2] row_mask:0xf bank_mask:0xf bound_ctrl:1
	v_add_u32_dpp v177, v177, v177 quad_perm:[1,0,3,2] row_mask:0xf bank_mask:0xf bound_ctrl:1
	v_add_u32_dpp v178, v178, v178 quad_perm:[1,0,3,2] row_mask:0xf bank_mask:0xf bound_ctrl:1
	v_add_u32_dpp v179, v179, v179 quad_perm:[1,0,3,2] row_mask:0xf bank_mask:0xf bound_ctrl:1
	v_add_u32_dpp v176, v176, v176 quad_perm:[2,3,0,1] row_mask:0xf bank_mask:0xf bound_ctrl:1
	v_add_u32_dpp v177, v177, v177 quad_perm:[2,3,0,1] row_mask:0xf bank_mask:0xf bound_ctrl:1
	v_add_u32_dpp v178, v178, v178 quad_perm:[2,3,0,1] row_mask:0xf bank_mask:0xf bound_ctrl:1
	v_add_u32_dpp v179, v179, v179 quad_perm:[2,3,0,1] row_mask:0xf bank_mask:0xf bound_ctrl:1
	v_add_u32_dpp v176, v176, v176 row_half_mirror row_mask:0xf bank_mask:0xf bound_ctrl:1
	v_add_u32_dpp v177, v177, v177 row_half_mirror row_mask:0xf bank_mask:0xf bound_ctrl:1
	v_add_u32_dpp v178, v178, v178 row_half_mirror row_mask:0xf bank_mask:0xf bound_ctrl:1
	v_add_u32_dpp v179, v179, v179 row_half_mirror row_mask:0xf bank_mask:0xf bound_ctrl:1
	v_add_u32_dpp v176, v176, v176 row_mirror row_mask:0xf bank_mask:0xf bound_ctrl:1
	v_add_u32_dpp v177, v177, v177 row_mirror row_mask:0xf bank_mask:0xf bound_ctrl:1
	v_add_u32_dpp v178, v178, v178 row_mirror row_mask:0xf bank_mask:0xf bound_ctrl:1
	v_add_u32_dpp v179, v179, v179 row_mirror row_mask:0xf bank_mask:0xf bound_ctrl:1
	v_cndmask_b32_e64 v152, v176, v177, s[82:83]
	v_cndmask_b32_e64 v152, v152, v178, s[84:85]
	v_cndmask_b32_e64 v152, v152, v179, s[86:87]
	s_waitcnt vmcnt(8)
	s_branch .Lp11a_gelu
; DI float gelu_t(float x) { float u = 0.7978845608028654f * (x + 0.044715f * x * x * x); float e = __expf(2.f * u); float t = 1.f - 2.f / (1.f + e); return 0.5f * x * (1.f + t); }
; DI void phase11a(const Params& P, char* smem_all) {
;     ...
; #pragma unroll
;       for (int gi = 0; gi < 6; ++gi) {
;         if (gi < ng) {
;           int d = 0;
; #pragma unroll
;           for (int c = 0; c < 4; ++c) {
;             d = __builtin_amdgcn_sdot4((int)u[gi][c].x, (int)xr[c].x, d, false);
;             d = __builtin_amdgcn_sdot4((int)u[gi][c].y, (int)xr[c].y, d, false);
;             d = __builtin_amdgcn_sdot4((int)u[gi][c].z, (int)xr[c].z, d, false);
;             d = __builtin_amdgcn_sdot4((int)u[gi][c].w, (int)xr[c].w, d, false);
;           }
;           d = dpp_row_sum_i(d);
;           const float dot = (float)d * (su[gi] * sx);
;           const float w = gl[gi] * gelu_t(dot) * sv[gi];
.Lp11a_d5:
	s_waitcnt vmcnt(26)
	v_mov_b32_e32 v176, 0
	v_dot4c_i32_i8_e32 v176, v48, v16
	v_dot4c_i32_i8_e32 v176, v49, v17
	v_dot4c_i32_i8_e32 v176, v50, v18
	v_dot4c_i32_i8_e32 v176, v51, v19
	v_dot4c_i32_i8_e32 v176, v52, v20
	v_dot4c_i32_i8_e32 v176, v53, v21
	v_dot4c_i32_i8_e32 v176, v54, v22
	v_dot4c_i32_i8_e32 v176, v55, v23
	v_dot4c_i32_i8_e32 v176, v56, v24
	v_dot4c_i32_i8_e32 v176, v57, v25
	v_dot4c_i32_i8_e32 v176, v58, v26
	v_dot4c_i32_i8_e32 v176, v59, v27
	v_dot4c_i32_i8_e32 v176, v60, v28
	v_dot4c_i32_i8_e32 v176, v61, v29
	v_dot4c_i32_i8_e32 v176, v62, v30
	v_dot4c_i32_i8_e32 v176, v63, v31
	s_waitcnt vmcnt(22)
	v_mov_b32_e32 v177, 0
	v_dot4c_i32_i8_e32 v177, v64, v16
	v_dot4c_i32_i8_e32 v177, v65, v17
	v_dot4c_i32_i8_e32 v177, v66, v18
	v_dot4c_i32_i8_e32 v177, v67, v19
	v_dot4c_i32_i8_e32 v177, v68, v20
	v_dot4c_i32_i8_e32 v177, v69, v21
	v_dot4c_i32_i8_e32 v177, v70, v22
	v_dot4c_i32_i8_e32 v177, v71, v23
	v_dot4c_i32_i8_e32 v177, v72, v24
	v_dot4c_i32_i8_e32 v177, v73, v25
	v_dot4c_i32_i8_e32 v177, v74, v26
	v_dot4c_i32_i8_e32 v177, v75, v27
	v_dot4c_i32_i8_e32 v177, v76, v28
	v_dot4c_i32_i8_e32 v177, v77, v29
	v_dot4c_i32_i8_e32 v177, v78, v30
	v_dot4c_i32_i8_e32 v177, v79, v31
	s_waitcnt vmcnt(18)
	v_mov_b32_e32 v178, 0
	v_dot4c_i32_i8_e32 v178, v80, v16
	v_dot4c_i32_i8_e32 v178, v81, v17
	v_dot4c_i32_i8_e32 v178, v82, v18
	v_dot4c_i32_i8_e32 v178, v83, v19
	v_dot4c_i32_i8_e32 v178, v84, v20
	v_dot4c_i32_i8_e32 v178, v85, v21
	v_dot4c_i32_i8_e32 v178, v86, v22
	v_dot4c_i32_i8_e32 v178, v87, v23
	v_dot4c_i32_i8_e32 v178, v88, v24
	v_dot4c_i32_i8_e32 v178, v89, v25
	v_dot4c_i32_i8_e32 v178, v90, v26
	v_dot4c_i32_i8_e32 v178, v91, v27
	v_dot4c_i32_i8_e32 v178, v92, v28
	v_dot4c_i32_i8_e32 v178, v93, v29
	v_dot4c_i32_i8_e32 v178, v94, v30
	v_dot4c_i32_i8_e32 v178, v95, v31
	s_waitcnt vmcnt(14)
	v_mov_b32_e32 v179, 0
	v_dot4c_i32_i8_e32 v179, v96, v16
	v_dot4c_i32_i8_e32 v179, v97, v17
	v_dot4c_i32_i8_e32 v179, v98, v18
	v_dot4c_i32_i8_e32 v179, v99, v19
	v_dot4c_i32_i8_e32 v179, v100, v20
	v_dot4c_i32_i8_e32 v179, v101, v21
	v_dot4c_i32_i8_e32 v179, v102, v22
	v_dot4c_i32_i8_e32 v179, v103, v23
	v_dot4c_i32_i8_e32 v179, v104, v24
	v_dot4c_i32_i8_e32 v179, v105, v25
	v_dot4c_i32_i8_e32 v179, v106, v26
	v_dot4c_i32_i8_e32 v179, v107, v27
	v_dot4c_i32_i8_e32 v179, v108, v28
	v_dot4c_i32_i8_e32 v179, v109, v29
	v_dot4c_i32_i8_e32 v179, v110, v30
	v_dot4c_i32_i8_e32 v179, v111, v31
	s_waitcnt vmcnt(10)
	v_mov_b32_e32 v180, 0
	v_dot4c_i32_i8_e32 v180, v112, v16
	v_dot4c_i32_i8_e32 v180, v113, v17
	v_dot4c_i32_i8_e32 v180, v114, v18
	v_dot4c_i32_i8_e32 v180, v115, v19
	v_dot4c_i32_i8_e32 v180, v116, v20
	v_dot4c_i32_i8_e32 v180, v117, v21
	v_dot4c_i32_i8_e32 v180, v118, v22
	v_dot4c_i32_i8_e32 v180, v119, v23
	v_dot4c_i32_i8_e32 v180, v120, v24
	v_dot4c_i32_i8_e32 v180, v121, v25
	v_dot4c_i32_i8_e32 v180, v122, v26
	v_dot4c_i32_i8_e32 v180, v123, v27
	v_dot4c_i32_i8_e32 v180, v124, v28
	v_dot4c_i32_i8_e32 v180, v125, v29
	v_dot4c_i32_i8_e32 v180, v126, v30
	v_dot4c_i32_i8_e32 v180, v127, v31
	s_nop 2
	v_add_u32_dpp v176, v176, v176 quad_perm:[1,0,3,2] row_mask:0xf bank_mask:0xf bound_ctrl:1
	v_add_u32_dpp v177, v177, v177 quad_perm:[1,0,3,2] row_mask:0xf bank_mask:0xf bound_ctrl:1
	v_add_u32_dpp v178, v178, v178 quad_perm:[1,0,3,2] row_mask:0xf bank_mask:0xf bound_ctrl:1
	v_add_u32_dpp v179, v179, v179 quad_perm:[1,0,3,2] row_mask:0xf bank_mask:0xf bound_ctrl:1
	v_add_u32_dpp v180, v180, v180 quad_perm:[1,0,3,2] row_mask:0xf bank_mask:0xf bound_ctrl:1
	v_add_u32_dpp v176, v176, v176 quad_perm:[2,3,0,1] row_mask:0xf bank_mask:0xf bound_ctrl:1
	v_add_u32_dpp v177, v177, v177 quad_perm:[2,3,0,1] row_mask:0xf bank_mask:0xf bound_ctrl:1
	v_add_u32_dpp v178, v178, v178 quad_perm:[2,3,0,1] row_mask:0xf bank_mask:0xf bound_ctrl:1
	v_add_u32_dpp v179, v179, v179 quad_perm:[2,3,0,1] row_mask:0xf bank_mask:0xf bound_ctrl:1
	v_add_u32_dpp v180, v180, v180 quad_perm:[2,3,0,1] row_mask:0xf bank_mask:0xf bound_ctrl:1
	v_add_u32_dpp v176, v176, v176 row_half_mirror row_mask:0xf bank_mask:0xf bound_ctrl:1
	v_add_u32_dpp v177, v177, v177 row_half_mirror row_mask:0xf bank_mask:0xf bound_ctrl:1
	v_add_u32_dpp v178, v178, v178 row_half_mirror row_mask:0xf bank_mask:0xf bound_ctrl:1
	v_add_u32_dpp v179, v179, v179 row_half_mirror row_mask:0xf bank_mask:0xf bound_ctrl:1
	v_add_u32_dpp v180, v180, v180 row_half_mirror row_mask:0xf bank_mask:0xf bound_ctrl:1
	v_add_u32_dpp v176, v176, v176 row_mirror row_mask:0xf bank_mask:0xf bound_ctrl:1
	v_add_u32_dpp v177, v177, v177 row_mirror row_mask:0xf bank_mask:0xf bound_ctrl:1
	v_add_u32_dpp v178, v178, v178 row_mirror row_mask:0xf bank_mask:0xf bound_ctrl:1
	v_add_u32_dpp v179, v179, v179 row_mirror row_mask:0xf bank_mask:0xf bound_ctrl:1
	v_add_u32_dpp v180, v180, v180 row_mirror row_mask:0xf bank_mask:0xf bound_ctrl:1
	v_cndmask_b32_e64 v152, v176, v177, s[82:83]
	v_cndmask_b32_e64 v152, v152, v178, s[84:85]
	v_cndmask_b32_e64 v152, v152, v179, s[86:87]
	v_cndmask_b32_e64 v152, v152, v180, s[88:89]
	s_waitcnt vmcnt(8)
	s_branch .Lp11a_gelu
; DI float gelu_t(float x) { float u = 0.7978845608028654f * (x + 0.044715f * x * x * x); float e = __expf(2.f * u); float t = 1.f - 2.f / (1.f + e); return 0.5f * x * (1.f + t); }
; DI void phase11a(const Params& P, char* smem_all) {
;     ...
; #pragma unroll
;       for (int gi = 0; gi < 6; ++gi) {
;         if (gi < ng) {
;           int d = 0;
; #pragma unroll
;           for (int c = 0; c < 4; ++c) {
;             d = __builtin_amdgcn_sdot4((int)u[gi][c].x, (int)xr[c].x, d, false);
;             d = __builtin_amdgcn_sdot4((int)u[gi][c].y, (int)xr[c].y, d, false);
;             d = __builtin_amdgcn_sdot4((int)u[gi][c].z, (int)xr[c].z, d, false);
;             d = __builtin_amdgcn_sdot4((int)u[gi][c].w, (int)xr[c].w, d, false);
;           }
;           d = dpp_row_sum_i(d);
;           const float dot = (float)d * (su[gi] * sx);
;           const float w = gl[gi] * gelu_t(dot) * sv[gi];
.Lp11a_d3:
	s_waitcnt vmcnt(18)
	v_mov_b32_e32 v176, 0
	v_dot4c_i32_i8_e32 v176, v48, v16
	v_dot4c_i32_i8_e32 v176, v49, v17
	v_dot4c_i32_i8_e32 v176, v50, v18
	v_dot4c_i32_i8_e32 v176, v51, v19
	v_dot4c_i32_i8_e32 v176, v52, v20
	v_dot4c_i32_i8_e32 v176, v53, v21
	v_dot4c_i32_i8_e32 v176, v54, v22
	v_dot4c_i32_i8_e32 v176, v55, v23
	v_dot4c_i32_i8_e32 v176, v56, v24
	v_dot4c_i32_i8_e32 v176, v57, v25
	v_dot4c_i32_i8_e32 v176, v58, v26
	v_dot4c_i32_i8_e32 v176, v59, v27
	v_dot4c_i32_i8_e32 v176, v60, v28
	v_dot4c_i32_i8_e32 v176, v61, v29
	v_dot4c_i32_i8_e32 v176, v62, v30
	v_dot4c_i32_i8_e32 v176, v63, v31
	s_waitcnt vmcnt(14)
	v_mov_b32_e32 v177, 0
	v_dot4c_i32_i8_e32 v177, v64, v16
	v_dot4c_i32_i8_e32 v177, v65, v17
	v_dot4c_i32_i8_e32 v177, v66, v18
	v_dot4c_i32_i8_e32 v177, v67, v19
	v_dot4c_i32_i8_e32 v177, v68, v20
	v_dot4c_i32_i8_e32 v177, v69, v21
	v_dot4c_i32_i8_e32 v177, v70, v22
	v_dot4c_i32_i8_e32 v177, v71, v23
	v_dot4c_i32_i8_e32 v177, v72, v24
	v_dot4c_i32_i8_e32 v177, v73, v25
	v_dot4c_i32_i8_e32 v177, v74, v26
	v_dot4c_i32_i8_e32 v177, v75, v27
	v_dot4c_i32_i8_e32 v177, v76, v28
	v_dot4c_i32_i8_e32 v177, v77, v29
	v_dot4c_i32_i8_e32 v177, v78, v30
	v_dot4c_i32_i8_e32 v177, v79, v31
	s_waitcnt vmcnt(10)
	v_mov_b32_e32 v178, 0
	v_dot4c_i32_i8_e32 v178, v80, v16
	v_dot4c_i32_i8_e32 v178, v81, v17
	v_dot4c_i32_i8_e32 v178, v82, v18
	v_dot4c_i32_i8_e32 v178, v83, v19
	v_dot4c_i32_i8_e32 v178, v84, v20
	v_dot4c_i32_i8_e32 v178, v85, v21
	v_dot4c_i32_i8_e32 v178, v86, v22
	v_dot4c_i32_i8_e32 v178, v87, v23
	v_dot4c_i32_i8_e32 v178, v88, v24
	v_dot4c_i32_i8_e32 v178, v89, v25
	v_dot4c_i32_i8_e32 v178, v90, v26
	v_dot4c_i32_i8_e32 v178, v91, v27
	v_dot4c_i32_i8_e32 v178, v92, v28
	v_dot4c_i32_i8_e32 v178, v93, v29
	v_dot4c_i32_i8_e32 v178, v94, v30
	v_dot4c_i32_i8_e32 v178, v95, v31
	s_nop 2
	v_add_u32_dpp v176, v176, v176 quad_perm:[1,0,3,2] row_mask:0xf bank_mask:0xf bound_ctrl:1
	v_add_u32_dpp v177, v177, v177 quad_perm:[1,0,3,2] row_mask:0xf bank_mask:0xf bound_ctrl:1
	v_add_u32_dpp v178, v178, v178 quad_perm:[1,0,3,2] row_mask:0xf bank_mask:0xf bound_ctrl:1
	v_add_u32_dpp v176, v176, v176 quad_perm:[2,3,0,1] row_mask:0xf bank_mask:0xf bound_ctrl:1
	v_add_u32_dpp v177, v177, v177 quad_perm:[2,3,0,1] row_mask:0xf bank_mask:0xf bound_ctrl:1
	v_add_u32_dpp v178, v178, v178 quad_perm:[2,3,0,1] row_mask:0xf bank_mask:0xf bound_ctrl:1
	v_add_u32_dpp v176, v176, v176 row_half_mirror row_mask:0xf bank_mask:0xf bound_ctrl:1
	v_add_u32_dpp v177, v177, v177 row_half_mirror row_mask:0xf bank_mask:0xf bound_ctrl:1
	v_add_u32_dpp v178, v178, v178 row_half_mirror row_mask:0xf bank_mask:0xf bound_ctrl:1
	v_add_u32_dpp v176, v176, v176 row_mirror row_mask:0xf bank_mask:0xf bound_ctrl:1
	v_add_u32_dpp v177, v177, v177 row_mirror row_mask:0xf bank_mask:0xf bound_ctrl:1
	v_add_u32_dpp v178, v178, v178 row_mirror row_mask:0xf bank_mask:0xf bound_ctrl:1
	v_cndmask_b32_e64 v152, v176, v177, s[82:83]
	v_cndmask_b32_e64 v152, v152, v178, s[84:85]
	s_waitcnt vmcnt(8)
	s_branch .Lp11a_gelu
.Lp11a_d6:
	s_waitcnt vmcnt(30)
	v_mov_b32_e32 v176, 0
	v_dot4c_i32_i8_e32 v176, v48, v16
	v_dot4c_i32_i8_e32 v176, v49, v17
	v_dot4c_i32_i8_e32 v176, v50, v18
	v_dot4c_i32_i8_e32 v176, v51, v19
	v_dot4c_i32_i8_e32 v176, v52, v20
	v_dot4c_i32_i8_e32 v176, v53, v21
	v_dot4c_i32_i8_e32 v176, v54, v22
	v_dot4c_i32_i8_e32 v176, v55, v23
	v_dot4c_i32_i8_e32 v176, v56, v24
	v_dot4c_i32_i8_e32 v176, v57, v25
	v_dot4c_i32_i8_e32 v176, v58, v26
	v_dot4c_i32_i8_e32 v176, v59, v27
	v_dot4c_i32_i8_e32 v176, v60, v28
	v_dot4c_i32_i8_e32 v176, v61, v29
	v_dot4c_i32_i8_e32 v176, v62, v30
	v_dot4c_i32_i8_e32 v176, v63, v31
	s_waitcnt vmcnt(26)
	v_mov_b32_e32 v177, 0
	v_dot4c_i32_i8_e32 v177, v64, v16
	v_dot4c_i32_i8_e32 v177, v65, v17
	v_dot4c_i32_i8_e32 v177, v66, v18
	v_dot4c_i32_i8_e32 v177, v67, v19
	v_dot4c_i32_i8_e32 v177, v68, v20
	v_dot4c_i32_i8_e32 v177, v69, v21
	v_dot4c_i32_i8_e32 v177, v70, v22
	v_dot4c_i32_i8_e32 v177, v71, v23
	v_dot4c_i32_i8_e32 v177, v72, v24
	v_dot4c_i32_i8_e32 v177, v73, v25
	v_dot4c_i32_i8_e32 v177, v74, v26
	v_dot4c_i32_i8_e32 v177, v75, v27
	v_dot4c_i32_i8_e32 v177, v76, v28
	v_dot4c_i32_i8_e32 v177, v77, v29
	v_dot4c_i32_i8_e32 v177, v78, v30
	v_dot4c_i32_i8_e32 v177, v79, v31
	s_waitcnt vmcnt(22)
	v_mov_b32_e32 v178, 0
	v_dot4c_i32_i8_e32 v178, v80, v16
	v_dot4c_i32_i8_e32 v178, v81, v17
	v_dot4c_i32_i8_e32 v178, v82, v18
	v_dot4c_i32_i8_e32 v178, v83, v19
	v_dot4c_i32_i8_e32 v178, v84, v20
	v_dot4c_i32_i8_e32 v178, v85, v21
	v_dot4c_i32_i8_e32 v178, v86, v22
	v_dot4c_i32_i8_e32 v178, v87, v23
	v_dot4c_i32_i8_e32 v178, v88, v24
	v_dot4c_i32_i8_e32 v178, v89, v25
	v_dot4c_i32_i8_e32 v178, v90, v26
	v_dot4c_i32_i8_e32 v178, v91, v27
	v_dot4c_i32_i8_e32 v178, v92, v28
	v_dot4c_i32_i8_e32 v178, v93, v29
	v_dot4c_i32_i8_e32 v178, v94, v30
	v_dot4c_i32_i8_e32 v178, v95, v31
	s_waitcnt vmcnt(18)
	v_mov_b32_e32 v179, 0
	v_dot4c_i32_i8_e32 v179, v96, v16
	v_dot4c_i32_i8_e32 v179, v97, v17
	v_dot4c_i32_i8_e32 v179, v98, v18
	v_dot4c_i32_i8_e32 v179, v99, v19
	v_dot4c_i32_i8_e32 v179, v100, v20
	v_dot4c_i32_i8_e32 v179, v101, v21
	v_dot4c_i32_i8_e32 v179, v102, v22
	v_dot4c_i32_i8_e32 v179, v103, v23
	v_dot4c_i32_i8_e32 v179, v104, v24
	v_dot4c_i32_i8_e32 v179, v105, v25
	v_dot4c_i32_i8_e32 v179, v106, v26
	v_dot4c_i32_i8_e32 v179, v107, v27
	v_dot4c_i32_i8_e32 v179, v108, v28
	v_dot4c_i32_i8_e32 v179, v109, v29
	v_dot4c_i32_i8_e32 v179, v110, v30
	v_dot4c_i32_i8_e32 v179, v111, v31
	s_waitcnt vmcnt(14)
; DI float gelu_t(float x) { float u = 0.7978845608028654f * (x + 0.044715f * x * x * x); float e = __expf(2.f * u); float t = 1.f - 2.f / (1.f + e); return 0.5f * x * (1.f + t); }
; DI void phase11a(const Params& P, char* smem_all) {
;     ...
; #pragma unroll
;       for (int gi = 0; gi < 6; ++gi) {
;         if (gi < ng) {
;           int d = 0;
; #pragma unroll
;           for (int c = 0; c < 4; ++c) {
;             d = __builtin_amdgcn_sdot4((int)u[gi][c].x, (int)xr[c].x, d, false);
;             d = __builtin_amdgcn_sdot4((int)u[gi][c].y, (int)xr[c].y, d, false);
;             d = __builtin_amdgcn_sdot4((int)u[gi][c].z, (int)xr[c].z, d, false);
;             d = __builtin_amdgcn_sdot4((int)u[gi][c].w, (int)xr[c].w, d, false);
;           }
;           d = dpp_row_sum_i(d);
;           const float dot = (float)d * (su[gi] * sx);
;           const float w = gl[gi] * gelu_t(dot) * sv[gi];
	v_mov_b32_e32 v180, 0
	v_dot4c_i32_i8_e32 v180, v112, v16
	v_dot4c_i32_i8_e32 v180, v113, v17
	v_dot4c_i32_i8_e32 v180, v114, v18
	v_dot4c_i32_i8_e32 v180, v115, v19
	v_dot4c_i32_i8_e32 v180, v116, v20
	v_dot4c_i32_i8_e32 v180, v117, v21
	v_dot4c_i32_i8_e32 v180, v118, v22
	v_dot4c_i32_i8_e32 v180, v119, v23
	v_dot4c_i32_i8_e32 v180, v120, v24
	v_dot4c_i32_i8_e32 v180, v121, v25
	v_dot4c_i32_i8_e32 v180, v122, v26
	v_dot4c_i32_i8_e32 v180, v123, v27
	v_dot4c_i32_i8_e32 v180, v124, v28
	v_dot4c_i32_i8_e32 v180, v125, v29
	v_dot4c_i32_i8_e32 v180, v126, v30
	v_dot4c_i32_i8_e32 v180, v127, v31
	s_waitcnt vmcnt(10)
	v_mov_b32_e32 v181, 0
	v_dot4c_i32_i8_e32 v181, v128, v16
	v_dot4c_i32_i8_e32 v181, v129, v17
	v_dot4c_i32_i8_e32 v181, v130, v18
	v_dot4c_i32_i8_e32 v181, v131, v19
	v_dot4c_i32_i8_e32 v181, v132, v20
	v_dot4c_i32_i8_e32 v181, v133, v21
	v_dot4c_i32_i8_e32 v181, v134, v22
	v_dot4c_i32_i8_e32 v181, v135, v23
	v_dot4c_i32_i8_e32 v181, v136, v24
	v_dot4c_i32_i8_e32 v181, v137, v25
	v_dot4c_i32_i8_e32 v181, v138, v26
	v_dot4c_i32_i8_e32 v181, v139, v27
	v_dot4c_i32_i8_e32 v181, v140, v28
	v_dot4c_i32_i8_e32 v181, v141, v29
	v_dot4c_i32_i8_e32 v181, v142, v30
	v_dot4c_i32_i8_e32 v181, v143, v31
	s_nop 2
	v_add_u32_dpp v176, v176, v176 quad_perm:[1,0,3,2] row_mask:0xf bank_mask:0xf bound_ctrl:1
	v_add_u32_dpp v177, v177, v177 quad_perm:[1,0,3,2] row_mask:0xf bank_mask:0xf bound_ctrl:1
	v_add_u32_dpp v178, v178, v178 quad_perm:[1,0,3,2] row_mask:0xf bank_mask:0xf bound_ctrl:1
	v_add_u32_dpp v179, v179, v179 quad_perm:[1,0,3,2] row_mask:0xf bank_mask:0xf bound_ctrl:1
	v_add_u32_dpp v180, v180, v180 quad_perm:[1,0,3,2] row_mask:0xf bank_mask:0xf bound_ctrl:1
	v_add_u32_dpp v181, v181, v181 quad_perm:[1,0,3,2] row_mask:0xf bank_mask:0xf bound_ctrl:1
	v_add_u32_dpp v176, v176, v176 quad_perm:[2,3,0,1] row_mask:0xf bank_mask:0xf bound_ctrl:1
	v_add_u32_dpp v177, v177, v177 quad_perm:[2,3,0,1] row_mask:0xf bank_mask:0xf bound_ctrl:1
	v_add_u32_dpp v178, v178, v178 quad_perm:[2,3,0,1] row_mask:0xf bank_mask:0xf bound_ctrl:1
	v_add_u32_dpp v179, v179, v179 quad_perm:[2,3,0,1] row_mask:0xf bank_mask:0xf bound_ctrl:1
	v_add_u32_dpp v180, v180, v180 quad_perm:[2,3,0,1] row_mask:0xf bank_mask:0xf bound_ctrl:1
	v_add_u32_dpp v181, v181, v181 quad_perm:[2,3,0,1] row_mask:0xf bank_mask:0xf bound_ctrl:1
	v_add_u32_dpp v176, v176, v176 row_half_mirror row_mask:0xf bank_mask:0xf bound_ctrl:1
	v_add_u32_dpp v177, v177, v177 row_half_mirror row_mask:0xf bank_mask:0xf bound_ctrl:1
	v_add_u32_dpp v178, v178, v178 row_half_mirror row_mask:0xf bank_mask:0xf bound_ctrl:1
	v_add_u32_dpp v179, v179, v179 row_half_mirror row_mask:0xf bank_mask:0xf bound_ctrl:1
	v_add_u32_dpp v180, v180, v180 row_half_mirror row_mask:0xf bank_mask:0xf bound_ctrl:1
	v_add_u32_dpp v181, v181, v181 row_half_mirror row_mask:0xf bank_mask:0xf bound_ctrl:1
	v_add_u32_dpp v176, v176, v176 row_mirror row_mask:0xf bank_mask:0xf bound_ctrl:1
	v_add_u32_dpp v177, v177, v177 row_mirror row_mask:0xf bank_mask:0xf bound_ctrl:1
	v_add_u32_dpp v178, v178, v178 row_mirror row_mask:0xf bank_mask:0xf bound_ctrl:1
	v_add_u32_dpp v179, v179, v179 row_mirror row_mask:0xf bank_mask:0xf bound_ctrl:1
	v_add_u32_dpp v180, v180, v180 row_mirror row_mask:0xf bank_mask:0xf bound_ctrl:1
	v_add_u32_dpp v181, v181, v181 row_mirror row_mask:0xf bank_mask:0xf bound_ctrl:1
	v_cndmask_b32_e64 v152, v176, v177, s[82:83]
	v_cndmask_b32_e64 v152, v152, v178, s[84:85]
	v_cndmask_b32_e64 v152, v152, v179, s[86:87]
	v_cndmask_b32_e64 v152, v152, v180, s[88:89]
	v_cndmask_b32_e64 v152, v152, v181, s[90:91]
	s_waitcnt vmcnt(8)
	s_branch .Lp11a_gelu
.Lp11a_d2:
	s_waitcnt vmcnt(14)
	v_mov_b32_e32 v176, 0
	v_dot4c_i32_i8_e32 v176, v48, v16
	v_dot4c_i32_i8_e32 v176, v49, v17
	v_dot4c_i32_i8_e32 v176, v50, v18
	v_dot4c_i32_i8_e32 v176, v51, v19
	v_dot4c_i32_i8_e32 v176, v52, v20
	v_dot4c_i32_i8_e32 v176, v53, v21
	v_dot4c_i32_i8_e32 v176, v54, v22
	v_dot4c_i32_i8_e32 v176, v55, v23
	v_dot4c_i32_i8_e32 v176, v56, v24
	v_dot4c_i32_i8_e32 v176, v57, v25
	v_dot4c_i32_i8_e32 v176, v58, v26
	v_dot4c_i32_i8_e32 v176, v59, v27
	v_dot4c_i32_i8_e32 v176, v60, v28
	v_dot4c_i32_i8_e32 v176, v61, v29
	v_dot4c_i32_i8_e32 v176, v62, v30
	v_dot4c_i32_i8_e32 v176, v63, v31
	s_waitcnt vmcnt(10)
	v_mov_b32_e32 v177, 0
	v_dot4c_i32_i8_e32 v177, v64, v16
	v_dot4c_i32_i8_e32 v177, v65, v17
	v_dot4c_i32_i8_e32 v177, v66, v18
	v_dot4c_i32_i8_e32 v177, v67, v19
	v_dot4c_i32_i8_e32 v177, v68, v20
	v_dot4c_i32_i8_e32 v177, v69, v21
	v_dot4c_i32_i8_e32 v177, v70, v22
	v_dot4c_i32_i8_e32 v177, v71, v23
	v_dot4c_i32_i8_e32 v177, v72, v24
	v_dot4c_i32_i8_e32 v177, v73, v25
	v_dot4c_i32_i8_e32 v177, v74, v26
	v_dot4c_i32_i8_e32 v177, v75, v27
	v_dot4c_i32_i8_e32 v177, v76, v28
	v_dot4c_i32_i8_e32 v177, v77, v29
	v_dot4c_i32_i8_e32 v177, v78, v30
	v_dot4c_i32_i8_e32 v177, v79, v31
	s_nop 2
	v_add_u32_dpp v176, v176, v176 quad_perm:[1,0,3,2] row_mask:0xf bank_mask:0xf bound_ctrl:1
	v_add_u32_dpp v177, v177, v177 quad_perm:[1,0,3,2] row_mask:0xf bank_mask:0xf bound_ctrl:1
	s_nop 0
	v_add_u32_dpp v176, v176, v176 quad_perm:[2,3,0,1] row_mask:0xf bank_mask:0xf bound_ctrl:1
	v_add_u32_dpp v177, v177, v177 quad_perm:[2,3,0,1] row_mask:0xf bank_mask:0xf bound_ctrl:1
	s_nop 0
	v_add_u32_dpp v176, v176, v176 row_half_mirror row_mask:0xf bank_mask:0xf bound_ctrl:1
	v_add_u32_dpp v177, v177, v177 row_half_mirror row_mask:0xf bank_mask:0xf bound_ctrl:1
	s_nop 0
	v_add_u32_dpp v176, v176, v176 row_mirror row_mask:0xf bank_mask:0xf bound_ctrl:1
	v_add_u32_dpp v177, v177, v177 row_mirror row_mask:0xf bank_mask:0xf bound_ctrl:1
	s_nop 0
	v_cndmask_b32_e64 v152, v176, v177, s[82:83]
	s_waitcnt vmcnt(8)
	s_branch .Lp11a_gelu
; DI float gelu_t(float x) { float u = 0.7978845608028654f * (x + 0.044715f * x * x * x); float e = __expf(2.f * u); float t = 1.f - 2.f / (1.f + e); return 0.5f * x * (1.f + t); }
; DI void phase11a(const Params& P, char* smem_all) {
;     ...
; #pragma unroll
;       for (int gi = 0; gi < 6; ++gi) {
;         if (gi < ng) {
;           int d = 0;
; #pragma unroll
;           for (int c = 0; c < 4; ++c) {
;             d = __builtin_amdgcn_sdot4((int)u[gi][c].x, (int)xr[c].x, d, false);
;             d = __builtin_amdgcn_sdot4((int)u[gi][c].y, (int)xr[c].y, d, false);
;             d = __builtin_amdgcn_sdot4((int)u[gi][c].z, (int)xr[c].z, d, false);
;             d = __builtin_amdgcn_sdot4((int)u[gi][c].w, (int)xr[c].w, d, false);
;           }
;           d = dpp_row_sum_i(d);
;           const float dot = (float)d * (su[gi] * sx);
;           const float w = gl[gi] * gelu_t(dot) * sv[gi];
.Lp11a_later:
	s_waitcnt vmcnt(0)
	s_cmp_eq_u32 s13, 4
	s_cbranch_scc1 .Lp11a_l4
	s_cmp_eq_u32 s13, 5
	s_cbranch_scc1 .Lp11a_l5
	s_cmp_eq_u32 s13, 3
	s_cbranch_scc1 .Lp11a_l3
	s_cmp_eq_u32 s13, 6
	s_cbranch_scc1 .Lp11a_l6
	s_cmp_eq_u32 s13, 2
	s_cbranch_scc1 .Lp11a_l2
.Lp11a_l1:
	s_waitcnt vmcnt(2)
	v_mov_b32_e32 v176, 0
	v_dot4c_i32_i8_e32 v176, v48, v16
	v_dot4c_i32_i8_e32 v176, v49, v17
	v_dot4c_i32_i8_e32 v176, v50, v18
	v_dot4c_i32_i8_e32 v176, v51, v19
	v_dot4c_i32_i8_e32 v176, v52, v20
	v_dot4c_i32_i8_e32 v176, v53, v21
	v_dot4c_i32_i8_e32 v176, v54, v22
	v_dot4c_i32_i8_e32 v176, v55, v23
	v_dot4c_i32_i8_e32 v176, v56, v24
	v_dot4c_i32_i8_e32 v176, v57, v25
	v_dot4c_i32_i8_e32 v176, v58, v26
	v_dot4c_i32_i8_e32 v176, v59, v27
	v_dot4c_i32_i8_e32 v176, v60, v28
	v_dot4c_i32_i8_e32 v176, v61, v29
	v_dot4c_i32_i8_e32 v176, v62, v30
	v_dot4c_i32_i8_e32 v176, v63, v31
	s_nop 2
	v_add_u32_dpp v176, v176, v176 quad_perm:[1,0,3,2] row_mask:0xf bank_mask:0xf bound_ctrl:1
	s_nop 1
	v_add_u32_dpp v176, v176, v176 quad_perm:[2,3,0,1] row_mask:0xf bank_mask:0xf bound_ctrl:1
	s_nop 1
	v_add_u32_dpp v176, v176, v176 row_half_mirror row_mask:0xf bank_mask:0xf bound_ctrl:1
	s_nop 1
	v_add_u32_dpp v176, v176, v176 row_mirror row_mask:0xf bank_mask:0xf bound_ctrl:1
	s_nop 1
	v_mov_b32_e32 v152, v176
	s_waitcnt vmcnt(0)
	s_branch .Lp11a_gelu
.Lp11a_l4:
	s_waitcnt vmcnt(14)
	v_mov_b32_e32 v176, 0
	v_dot4c_i32_i8_e32 v176, v48, v16
	v_dot4c_i32_i8_e32 v176, v49, v17
	v_dot4c_i32_i8_e32 v176, v50, v18
	v_dot4c_i32_i8_e32 v176, v51, v19
	v_dot4c_i32_i8_e32 v176, v52, v20
	v_dot4c_i32_i8_e32 v176, v53, v21
	v_dot4c_i32_i8_e32 v176, v54, v22
	v_dot4c_i32_i8_e32 v176, v55, v23
	v_dot4c_i32_i8_e32 v176, v56, v24
	v_dot4c_i32_i8_e32 v176, v57, v25
	v_dot4c_i32_i8_e32 v176, v58, v26
	v_dot4c_i32_i8_e32 v176, v59, v27
	v_dot4c_i32_i8_e32 v176, v60, v28
	v_dot4c_i32_i8_e32 v176, v61, v29
	v_dot4c_i32_i8_e32 v176, v62, v30
	v_dot4c_i32_i8_e32 v176, v63, v31
	s_waitcnt vmcnt(10)
	v_mov_b32_e32 v177, 0
	v_dot4c_i32_i8_e32 v177, v64, v16
	v_dot4c_i32_i8_e32 v177, v65, v17
	v_dot4c_i32_i8_e32 v177, v66, v18
	v_dot4c_i32_i8_e32 v177, v67, v19
	v_dot4c_i32_i8_e32 v177, v68, v20
	v_dot4c_i32_i8_e32 v177, v69, v21
	v_dot4c_i32_i8_e32 v177, v70, v22
	v_dot4c_i32_i8_e32 v177, v71, v23
	v_dot4c_i32_i8_e32 v177, v72, v24
	v_dot4c_i32_i8_e32 v177, v73, v25
	v_dot4c_i32_i8_e32 v177, v74, v26
	v_dot4c_i32_i8_e32 v177, v75, v27
	v_dot4c_i32_i8_e32 v177, v76, v28
	v_dot4c_i32_i8_e32 v177, v77, v29
	v_dot4c_i32_i8_e32 v177, v78, v30
	v_dot4c_i32_i8_e32 v177, v79, v31
	s_waitcnt vmcnt(6)
	v_mov_b32_e32 v178, 0
	v_dot4c_i32_i8_e32 v178, v80, v16
	v_dot4c_i32_i8_e32 v178, v81, v17
	v_dot4c_i32_i8_e32 v178, v82, v18
	v_dot4c_i32_i8_e32 v178, v83, v19
	v_dot4c_i32_i8_e32 v178, v84, v20
	v_dot4c_i32_i8_e32 v178, v85, v21
	v_dot4c_i32_i8_e32 v178, v86, v22
	v_dot4c_i32_i8_e32 v178, v87, v23
	v_dot4c_i32_i8_e32 v178, v88, v24
	v_dot4c_i32_i8_e32 v178, v89, v25
	v_dot4c_i32_i8_e32 v178, v90, v26
	v_dot4c_i32_i8_e32 v178, v91, v27
	v_dot4c_i32_i8_e32 v178, v92, v28
	v_dot4c_i32_i8_e32 v178, v93, v29
	v_dot4c_i32_i8_e32 v178, v94, v30
	v_dot4c_i32_i8_e32 v178, v95, v31
	s_waitcnt vmcnt(2)
	v_mov_b32_e32 v179, 0
	v_dot4c_i32_i8_e32 v179, v96, v16
	v_dot4c_i32_i8_e32 v179, v97, v17
	v_dot4c_i32_i8_e32 v179, v98, v18
	v_dot4c_i32_i8_e32 v179, v99, v19
	v_dot4c_i32_i8_e32 v179, v100, v20
	v_dot4c_i32_i8_e32 v179, v101, v21
	v_dot4c_i32_i8_e32 v179, v102, v22
	v_dot4c_i32_i8_e32 v179, v103, v23
	v_dot4c_i32_i8_e32 v179, v104, v24
	v_dot4c_i32_i8_e32 v179, v105, v25
	v_dot4c_i32_i8_e32 v179, v106, v26
	v_dot4c_i32_i8_e32 v179, v107, v27
	v_dot4c_i32_i8_e32 v179, v108, v28
	v_dot4c_i32_i8_e32 v179, v109, v29
	v_dot4c_i32_i8_e32 v179, v110, v30
	v_dot4c_i32_i8_e32 v179, v111, v31
	s_nop 2
	v_add_u32_dpp v176, v176, v176 quad_perm:[1,0,3,2] row_mask:0xf bank_mask:0xf bound_ctrl:1
	v_add_u32_dpp v177, v177, v177 quad_perm:[1,0,3,2] row_mask:0xf bank_mask:0xf bound_ctrl:1
	v_add_u32_dpp v178, v178, v178 quad_perm:[1,0,3,2] row_mask:0xf bank_mask:0xf bound_ctrl:1
	v_add_u32_dpp v179, v179, v179 quad_perm:[1,0,3,2] row_mask:0xf bank_mask:0xf bound_ctrl:1
	v_add_u32_dpp v176, v176, v176 quad_perm:[2,3,0,1] row_mask:0xf bank_mask:0xf bound_ctrl:1
	v_add_u32_dpp v177, v177, v177 quad_perm:[2,3,0,1] row_mask:0xf bank_mask:0xf bound_ctrl:1
	v_add_u32_dpp v178, v178, v178 quad_perm:[2,3,0,1] row_mask:0xf bank_mask:0xf bound_ctrl:1
	v_add_u32_dpp v179, v179, v179 quad_perm:[2,3,0,1] row_mask:0xf bank_mask:0xf bound_ctrl:1
	v_add_u32_dpp v176, v176, v176 row_half_mirror row_mask:0xf bank_mask:0xf bound_ctrl:1
	v_add_u32_dpp v177, v177, v177 row_half_mirror row_mask:0xf bank_mask:0xf bound_ctrl:1
	v_add_u32_dpp v178, v178, v178 row_half_mirror row_mask:0xf bank_mask:0xf bound_ctrl:1
	v_add_u32_dpp v179, v179, v179 row_half_mirror row_mask:0xf bank_mask:0xf bound_ctrl:1
	v_add_u32_dpp v176, v176, v176 row_mirror row_mask:0xf bank_mask:0xf bound_ctrl:1
	v_add_u32_dpp v177, v177, v177 row_mirror row_mask:0xf bank_mask:0xf bound_ctrl:1
	v_add_u32_dpp v178, v178, v178 row_mirror row_mask:0xf bank_mask:0xf bound_ctrl:1
	v_add_u32_dpp v179, v179, v179 row_mirror row_mask:0xf bank_mask:0xf bound_ctrl:1
	v_cndmask_b32_e64 v152, v176, v177, s[82:83]
	v_cndmask_b32_e64 v152, v152, v178, s[84:85]
	v_cndmask_b32_e64 v152, v152, v179, s[86:87]
	s_waitcnt vmcnt(0)
	s_branch .Lp11a_gelu
; DI float gelu_t(float x) { float u = 0.7978845608028654f * (x + 0.044715f * x * x * x); float e = __expf(2.f * u); float t = 1.f - 2.f / (1.f + e); return 0.5f * x * (1.f + t); }
; DI void phase11a(const Params& P, char* smem_all) {
;     ...
; #pragma unroll
;       for (int gi = 0; gi < 6; ++gi) {
;         if (gi < ng) {
;           int d = 0;
; #pragma unroll
;           for (int c = 0; c < 4; ++c) {
;             d = __builtin_amdgcn_sdot4((int)u[gi][c].x, (int)xr[c].x, d, false);
;             d = __builtin_amdgcn_sdot4((int)u[gi][c].y, (int)xr[c].y, d, false);
;             d = __builtin_amdgcn_sdot4((int)u[gi][c].z, (int)xr[c].z, d, false);
;             d = __builtin_amdgcn_sdot4((int)u[gi][c].w, (int)xr[c].w, d, false);
;           }
;           d = dpp_row_sum_i(d);
;           const float dot = (float)d * (su[gi] * sx);
;           const float w = gl[gi] * gelu_t(dot) * sv[gi];
.Lp11a_l5:
	s_waitcnt vmcnt(18)
	v_mov_b32_e32 v176, 0
	v_dot4c_i32_i8_e32 v176, v48, v16
	v_dot4c_i32_i8_e32 v176, v49, v17
	v_dot4c_i32_i8_e32 v176, v50, v18
	v_dot4c_i32_i8_e32 v176, v51, v19
	v_dot4c_i32_i8_e32 v176, v52, v20
	v_dot4c_i32_i8_e32 v176, v53, v21
	v_dot4c_i32_i8_e32 v176, v54, v22
	v_dot4c_i32_i8_e32 v176, v55, v23
	v_dot4c_i32_i8_e32 v176, v56, v24
	v_dot4c_i32_i8_e32 v176, v57, v25
	v_dot4c_i32_i8_e32 v176, v58, v26
	v_dot4c_i32_i8_e32 v176, v59, v27
	v_dot4c_i32_i8_e32 v176, v60, v28
	v_dot4c_i32_i8_e32 v176, v61, v29
	v_dot4c_i32_i8_e32 v176, v62, v30
	v_dot4c_i32_i8_e32 v176, v63, v31
	s_waitcnt vmcnt(14)
	v_mov_b32_e32 v177, 0
	v_dot4c_i32_i8_e32 v177, v64, v16
	v_dot4c_i32_i8_e32 v177, v65, v17
	v_dot4c_i32_i8_e32 v177, v66, v18
	v_dot4c_i32_i8_e32 v177, v67, v19
	v_dot4c_i32_i8_e32 v177, v68, v20
	v_dot4c_i32_i8_e32 v177, v69, v21
	v_dot4c_i32_i8_e32 v177, v70, v22
	v_dot4c_i32_i8_e32 v177, v71, v23
	v_dot4c_i32_i8_e32 v177, v72, v24
	v_dot4c_i32_i8_e32 v177, v73, v25
	v_dot4c_i32_i8_e32 v177, v74, v26
	v_dot4c_i32_i8_e32 v177, v75, v27
	v_dot4c_i32_i8_e32 v177, v76, v28
	v_dot4c_i32_i8_e32 v177, v77, v29
	v_dot4c_i32_i8_e32 v177, v78, v30
	v_dot4c_i32_i8_e32 v177, v79, v31
	s_waitcnt vmcnt(10)
	v_mov_b32_e32 v178, 0
	v_dot4c_i32_i8_e32 v178, v80, v16
	v_dot4c_i32_i8_e32 v178, v81, v17
	v_dot4c_i32_i8_e32 v178, v82, v18
	v_dot4c_i32_i8_e32 v178, v83, v19
	v_dot4c_i32_i8_e32 v178, v84, v20
	v_dot4c_i32_i8_e32 v178, v85, v21
	v_dot4c_i32_i8_e32 v178, v86, v22
	v_dot4c_i32_i8_e32 v178, v87, v23
	v_dot4c_i32_i8_e32 v178, v88, v24
	v_dot4c_i32_i8_e32 v178, v89, v25
	v_dot4c_i32_i8_e32 v178, v90, v26
	v_dot4c_i32_i8_e32 v178, v91, v27
	v_dot4c_i32_i8_e32 v178, v92, v28
	v_dot4c_i32_i8_e32 v178, v93, v29
	v_dot4c_i32_i8_e32 v178, v94, v30
	v_dot4c_i32_i8_e32 v178, v95, v31
	s_waitcnt vmcnt(6)
	v_mov_b32_e32 v179, 0
	v_dot4c_i32_i8_e32 v179, v96, v16
	v_dot4c_i32_i8_e32 v179, v97, v17
	v_dot4c_i32_i8_e32 v179, v98, v18
	v_dot4c_i32_i8_e32 v179, v99, v19
	v_dot4c_i32_i8_e32 v179, v100, v20
	v_dot4c_i32_i8_e32 v179, v101, v21
	v_dot4c_i32_i8_e32 v179, v102, v22
	v_dot4c_i32_i8_e32 v179, v103, v23
	v_dot4c_i32_i8_e32 v179, v104, v24
	v_dot4c_i32_i8_e32 v179, v105, v25
	v_dot4c_i32_i8_e32 v179, v106, v26
	v_dot4c_i32_i8_e32 v179, v107, v27
	v_dot4c_i32_i8_e32 v179, v108, v28
	v_dot4c_i32_i8_e32 v179, v109, v29
	v_dot4c_i32_i8_e32 v179, v110, v30
	v_dot4c_i32_i8_e32 v179, v111, v31
	s_waitcnt vmcnt(2)
	v_mov_b32_e32 v180, 0
	v_dot4c_i32_i8_e32 v180, v112, v16
	v_dot4c_i32_i8_e32 v180, v113, v17
	v_dot4c_i32_i8_e32 v180, v114, v18
	v_dot4c_i32_i8_e32 v180, v115, v19
	v_dot4c_i32_i8_e32 v180, v116, v20
	v_dot4c_i32_i8_e32 v180, v117, v21
	v_dot4c_i32_i8_e32 v180, v118, v22
	v_dot4c_i32_i8_e32 v180, v119, v23
	v_dot4c_i32_i8_e32 v180, v120, v24
	v_dot4c_i32_i8_e32 v180, v121, v25
	v_dot4c_i32_i8_e32 v180, v122, v26
	v_dot4c_i32_i8_e32 v180, v123, v27
	v_dot4c_i32_i8_e32 v180, v124, v28
	v_dot4c_i32_i8_e32 v180, v125, v29
	v_dot4c_i32_i8_e32 v180, v126, v30
	v_dot4c_i32_i8_e32 v180, v127, v31
	s_nop 2
	v_add_u32_dpp v176, v176, v176 quad_perm:[1,0,3,2] row_mask:0xf bank_mask:0xf bound_ctrl:1
	v_add_u32_dpp v177, v177, v177 quad_perm:[1,0,3,2] row_mask:0xf bank_mask:0xf bound_ctrl:1
	v_add_u32_dpp v178, v178, v178 quad_perm:[1,0,3,2] row_mask:0xf bank_mask:0xf bound_ctrl:1
	v_add_u32_dpp v179, v179, v179 quad_perm:[1,0,3,2] row_mask:0xf bank_mask:0xf bound_ctrl:1
	v_add_u32_dpp v180, v180, v180 quad_perm:[1,0,3,2] row_mask:0xf bank_mask:0xf bound_ctrl:1
	v_add_u32_dpp v176, v176, v176 quad_perm:[2,3,0,1] row_mask:0xf bank_mask:0xf bound_ctrl:1
	v_add_u32_dpp v177, v177, v177 quad_perm:[2,3,0,1] row_mask:0xf bank_mask:0xf bound_ctrl:1
	v_add_u32_dpp v178, v178, v178 quad_perm:[2,3,0,1] row_mask:0xf bank_mask:0xf bound_ctrl:1
	v_add_u32_dpp v179, v179, v179 quad_perm:[2,3,0,1] row_mask:0xf bank_mask:0xf bound_ctrl:1
	v_add_u32_dpp v180, v180, v180 quad_perm:[2,3,0,1] row_mask:0xf bank_mask:0xf bound_ctrl:1
	v_add_u32_dpp v176, v176, v176 row_half_mirror row_mask:0xf bank_mask:0xf bound_ctrl:1
	v_add_u32_dpp v177, v177, v177 row_half_mirror row_mask:0xf bank_mask:0xf bound_ctrl:1
	v_add_u32_dpp v178, v178, v178 row_half_mirror row_mask:0xf bank_mask:0xf bound_ctrl:1
	v_add_u32_dpp v179, v179, v179 row_half_mirror row_mask:0xf bank_mask:0xf bound_ctrl:1
	v_add_u32_dpp v180, v180, v180 row_half_mirror row_mask:0xf bank_mask:0xf bound_ctrl:1
	v_add_u32_dpp v176, v176, v176 row_mirror row_mask:0xf bank_mask:0xf bound_ctrl:1
	v_add_u32_dpp v177, v177, v177 row_mirror row_mask:0xf bank_mask:0xf bound_ctrl:1
	v_add_u32_dpp v178, v178, v178 row_mirror row_mask:0xf bank_mask:0xf bound_ctrl:1
	v_add_u32_dpp v179, v179, v179 row_mirror row_mask:0xf bank_mask:0xf bound_ctrl:1
	v_add_u32_dpp v180, v180, v180 row_mirror row_mask:0xf bank_mask:0xf bound_ctrl:1
	v_cndmask_b32_e64 v152, v176, v177, s[82:83]
	v_cndmask_b32_e64 v152, v152, v178, s[84:85]
	v_cndmask_b32_e64 v152, v152, v179, s[86:87]
	v_cndmask_b32_e64 v152, v152, v180, s[88:89]
	s_waitcnt vmcnt(0)
	s_branch .Lp11a_gelu
; DI float gelu_t(float x) { float u = 0.7978845608028654f * (x + 0.044715f * x * x * x); float e = __expf(2.f * u); float t = 1.f - 2.f / (1.f + e); return 0.5f * x * (1.f + t); }
; DI void phase11a(const Params& P, char* smem_all) {
;     ...
; #pragma unroll
;       for (int gi = 0; gi < 6; ++gi) {
;         if (gi < ng) {
;           int d = 0;
; #pragma unroll
;           for (int c = 0; c < 4; ++c) {
;             d = __builtin_amdgcn_sdot4((int)u[gi][c].x, (int)xr[c].x, d, false);
;             d = __builtin_amdgcn_sdot4((int)u[gi][c].y, (int)xr[c].y, d, false);
;             d = __builtin_amdgcn_sdot4((int)u[gi][c].z, (int)xr[c].z, d, false);
;             d = __builtin_amdgcn_sdot4((int)u[gi][c].w, (int)xr[c].w, d, false);
;           }
;           d = dpp_row_sum_i(d);
;           const float dot = (float)d * (su[gi] * sx);
;           const float w = gl[gi] * gelu_t(dot) * sv[gi];
.Lp11a_l3:
	s_waitcnt vmcnt(10)
	v_mov_b32_e32 v176, 0
	v_dot4c_i32_i8_e32 v176, v48, v16
	v_dot4c_i32_i8_e32 v176, v49, v17
	v_dot4c_i32_i8_e32 v176, v50, v18
	v_dot4c_i32_i8_e32 v176, v51, v19
	v_dot4c_i32_i8_e32 v176, v52, v20
	v_dot4c_i32_i8_e32 v176, v53, v21
	v_dot4c_i32_i8_e32 v176, v54, v22
	v_dot4c_i32_i8_e32 v176, v55, v23
	v_dot4c_i32_i8_e32 v176, v56, v24
	v_dot4c_i32_i8_e32 v176, v57, v25
	v_dot4c_i32_i8_e32 v176, v58, v26
	v_dot4c_i32_i8_e32 v176, v59, v27
	v_dot4c_i32_i8_e32 v176, v60, v28
	v_dot4c_i32_i8_e32 v176, v61, v29
	v_dot4c_i32_i8_e32 v176, v62, v30
	v_dot4c_i32_i8_e32 v176, v63, v31
	s_waitcnt vmcnt(6)
	v_mov_b32_e32 v177, 0
	v_dot4c_i32_i8_e32 v177, v64, v16
	v_dot4c_i32_i8_e32 v177, v65, v17
	v_dot4c_i32_i8_e32 v177, v66, v18
	v_dot4c_i32_i8_e32 v177, v67, v19
	v_dot4c_i32_i8_e32 v177, v68, v20
	v_dot4c_i32_i8_e32 v177, v69, v21
	v_dot4c_i32_i8_e32 v177, v70, v22
	v_dot4c_i32_i8_e32 v177, v71, v23
	v_dot4c_i32_i8_e32 v177, v72, v24
	v_dot4c_i32_i8_e32 v177, v73, v25
	v_dot4c_i32_i8_e32 v177, v74, v26
	v_dot4c_i32_i8_e32 v177, v75, v27
	v_dot4c_i32_i8_e32 v177, v76, v28
	v_dot4c_i32_i8_e32 v177, v77, v29
	v_dot4c_i32_i8_e32 v177, v78, v30
	v_dot4c_i32_i8_e32 v177, v79, v31
	s_waitcnt vmcnt(2)
	v_mov_b32_e32 v178, 0
	v_dot4c_i32_i8_e32 v178, v80, v16
	v_dot4c_i32_i8_e32 v178, v81, v17
	v_dot4c_i32_i8_e32 v178, v82, v18
	v_dot4c_i32_i8_e32 v178, v83, v19
	v_dot4c_i32_i8_e32 v178, v84, v20
	v_dot4c_i32_i8_e32 v178, v85, v21
	v_dot4c_i32_i8_e32 v178, v86, v22
	v_dot4c_i32_i8_e32 v178, v87, v23
	v_dot4c_i32_i8_e32 v178, v88, v24
	v_dot4c_i32_i8_e32 v178, v89, v25
	v_dot4c_i32_i8_e32 v178, v90, v26
	v_dot4c_i32_i8_e32 v178, v91, v27
	v_dot4c_i32_i8_e32 v178, v92, v28
	v_dot4c_i32_i8_e32 v178, v93, v29
	v_dot4c_i32_i8_e32 v178, v94, v30
	v_dot4c_i32_i8_e32 v178, v95, v31
	s_nop 2
	v_add_u32_dpp v176, v176, v176 quad_perm:[1,0,3,2] row_mask:0xf bank_mask:0xf bound_ctrl:1
	v_add_u32_dpp v177, v177, v177 quad_perm:[1,0,3,2] row_mask:0xf bank_mask:0xf bound_ctrl:1
	v_add_u32_dpp v178, v178, v178 quad_perm:[1,0,3,2] row_mask:0xf bank_mask:0xf bound_ctrl:1
	v_add_u32_dpp v176, v176, v176 quad_perm:[2,3,0,1] row_mask:0xf bank_mask:0xf bound_ctrl:1
	v_add_u32_dpp v177, v177, v177 quad_perm:[2,3,0,1] row_mask:0xf bank_mask:0xf bound_ctrl:1
	v_add_u32_dpp v178, v178, v178 quad_perm:[2,3,0,1] row_mask:0xf bank_mask:0xf bound_ctrl:1
	v_add_u32_dpp v176, v176, v176 row_half_mirror row_mask:0xf bank_mask:0xf bound_ctrl:1
	v_add_u32_dpp v177, v177, v177 row_half_mirror row_mask:0xf bank_mask:0xf bound_ctrl:1
	v_add_u32_dpp v178, v178, v178 row_half_mirror row_mask:0xf bank_mask:0xf bound_ctrl:1
	v_add_u32_dpp v176, v176, v176 row_mirror row_mask:0xf bank_mask:0xf bound_ctrl:1
	v_add_u32_dpp v177, v177, v177 row_mirror row_mask:0xf bank_mask:0xf bound_ctrl:1
	v_add_u32_dpp v178, v178, v178 row_mirror row_mask:0xf bank_mask:0xf bound_ctrl:1
	v_cndmask_b32_e64 v152, v176, v177, s[82:83]
	v_cndmask_b32_e64 v152, v152, v178, s[84:85]
	s_waitcnt vmcnt(0)
	s_branch .Lp11a_gelu
.Lp11a_l6:
	s_waitcnt vmcnt(22)
	v_mov_b32_e32 v176, 0
	v_dot4c_i32_i8_e32 v176, v48, v16
	v_dot4c_i32_i8_e32 v176, v49, v17
	v_dot4c_i32_i8_e32 v176, v50, v18
	v_dot4c_i32_i8_e32 v176, v51, v19
	v_dot4c_i32_i8_e32 v176, v52, v20
	v_dot4c_i32_i8_e32 v176, v53, v21
	v_dot4c_i32_i8_e32 v176, v54, v22
	v_dot4c_i32_i8_e32 v176, v55, v23
	v_dot4c_i32_i8_e32 v176, v56, v24
	v_dot4c_i32_i8_e32 v176, v57, v25
	v_dot4c_i32_i8_e32 v176, v58, v26
	v_dot4c_i32_i8_e32 v176, v59, v27
	v_dot4c_i32_i8_e32 v176, v60, v28
	v_dot4c_i32_i8_e32 v176, v61, v29
	v_dot4c_i32_i8_e32 v176, v62, v30
	v_dot4c_i32_i8_e32 v176, v63, v31
	s_waitcnt vmcnt(18)
	v_mov_b32_e32 v177, 0
	v_dot4c_i32_i8_e32 v177, v64, v16
	v_dot4c_i32_i8_e32 v177, v65, v17
	v_dot4c_i32_i8_e32 v177, v66, v18
	v_dot4c_i32_i8_e32 v177, v67, v19
	v_dot4c_i32_i8_e32 v177, v68, v20
	v_dot4c_i32_i8_e32 v177, v69, v21
	v_dot4c_i32_i8_e32 v177, v70, v22
	v_dot4c_i32_i8_e32 v177, v71, v23
	v_dot4c_i32_i8_e32 v177, v72, v24
	v_dot4c_i32_i8_e32 v177, v73, v25
	v_dot4c_i32_i8_e32 v177, v74, v26
	v_dot4c_i32_i8_e32 v177, v75, v27
	v_dot4c_i32_i8_e32 v177, v76, v28
	v_dot4c_i32_i8_e32 v177, v77, v29
	v_dot4c_i32_i8_e32 v177, v78, v30
	v_dot4c_i32_i8_e32 v177, v79, v31
	s_waitcnt vmcnt(14)
	v_mov_b32_e32 v178, 0
	v_dot4c_i32_i8_e32 v178, v80, v16
	v_dot4c_i32_i8_e32 v178, v81, v17
	v_dot4c_i32_i8_e32 v178, v82, v18
	v_dot4c_i32_i8_e32 v178, v83, v19
	v_dot4c_i32_i8_e32 v178, v84, v20
	v_dot4c_i32_i8_e32 v178, v85, v21
	v_dot4c_i32_i8_e32 v178, v86, v22
	v_dot4c_i32_i8_e32 v178, v87, v23
	v_dot4c_i32_i8_e32 v178, v88, v24
	v_dot4c_i32_i8_e32 v178, v89, v25
	v_dot4c_i32_i8_e32 v178, v90, v26
	v_dot4c_i32_i8_e32 v178, v91, v27
	v_dot4c_i32_i8_e32 v178, v92, v28
	v_dot4c_i32_i8_e32 v178, v93, v29
	v_dot4c_i32_i8_e32 v178, v94, v30
	v_dot4c_i32_i8_e32 v178, v95, v31
	s_waitcnt vmcnt(10)
	v_mov_b32_e32 v179, 0
	v_dot4c_i32_i8_e32 v179, v96, v16
	v_dot4c_i32_i8_e32 v179, v97, v17
	v_dot4c_i32_i8_e32 v179, v98, v18
	v_dot4c_i32_i8_e32 v179, v99, v19
	v_dot4c_i32_i8_e32 v179, v100, v20
	v_dot4c_i32_i8_e32 v179, v101, v21
	v_dot4c_i32_i8_e32 v179, v102, v22
	v_dot4c_i32_i8_e32 v179, v103, v23
	v_dot4c_i32_i8_e32 v179, v104, v24
	v_dot4c_i32_i8_e32 v179, v105, v25
	v_dot4c_i32_i8_e32 v179, v106, v26
	v_dot4c_i32_i8_e32 v179, v107, v27
	v_dot4c_i32_i8_e32 v179, v108, v28
	v_dot4c_i32_i8_e32 v179, v109, v29
	v_dot4c_i32_i8_e32 v179, v110, v30
	v_dot4c_i32_i8_e32 v179, v111, v31
	s_waitcnt vmcnt(6)
; DI float gelu_t(float x) { float u = 0.7978845608028654f * (x + 0.044715f * x * x * x); float e = __expf(2.f * u); float t = 1.f - 2.f / (1.f + e); return 0.5f * x * (1.f + t); }
; DI void phase11a(const Params& P, char* smem_all) {
;     ...
; #pragma unroll
;       for (int gi = 0; gi < 6; ++gi) {
;         if (gi < ng) {
;           int d = 0;
; #pragma unroll
;           for (int c = 0; c < 4; ++c) {
;             d = __builtin_amdgcn_sdot4((int)u[gi][c].x, (int)xr[c].x, d, false);
;             d = __builtin_amdgcn_sdot4((int)u[gi][c].y, (int)xr[c].y, d, false);
;             d = __builtin_amdgcn_sdot4((int)u[gi][c].z, (int)xr[c].z, d, false);
;             d = __builtin_amdgcn_sdot4((int)u[gi][c].w, (int)xr[c].w, d, false);
;           }
;           d = dpp_row_sum_i(d);
;           const float dot = (float)d * (su[gi] * sx);
;           const float w = gl[gi] * gelu_t(dot) * sv[gi];
	v_mov_b32_e32 v180, 0
	v_dot4c_i32_i8_e32 v180, v112, v16
	v_dot4c_i32_i8_e32 v180, v113, v17
	v_dot4c_i32_i8_e32 v180, v114, v18
	v_dot4c_i32_i8_e32 v180, v115, v19
	v_dot4c_i32_i8_e32 v180, v116, v20
	v_dot4c_i32_i8_e32 v180, v117, v21
	v_dot4c_i32_i8_e32 v180, v118, v22
	v_dot4c_i32_i8_e32 v180, v119, v23
	v_dot4c_i32_i8_e32 v180, v120, v24
	v_dot4c_i32_i8_e32 v180, v121, v25
	v_dot4c_i32_i8_e32 v180, v122, v26
	v_dot4c_i32_i8_e32 v180, v123, v27
	v_dot4c_i32_i8_e32 v180, v124, v28
	v_dot4c_i32_i8_e32 v180, v125, v29
	v_dot4c_i32_i8_e32 v180, v126, v30
	v_dot4c_i32_i8_e32 v180, v127, v31
	s_waitcnt vmcnt(2)
	v_mov_b32_e32 v181, 0
	v_dot4c_i32_i8_e32 v181, v128, v16
	v_dot4c_i32_i8_e32 v181, v129, v17
	v_dot4c_i32_i8_e32 v181, v130, v18
	v_dot4c_i32_i8_e32 v181, v131, v19
	v_dot4c_i32_i8_e32 v181, v132, v20
	v_dot4c_i32_i8_e32 v181, v133, v21
	v_dot4c_i32_i8_e32 v181, v134, v22
	v_dot4c_i32_i8_e32 v181, v135, v23
	v_dot4c_i32_i8_e32 v181, v136, v24
	v_dot4c_i32_i8_e32 v181, v137, v25
	v_dot4c_i32_i8_e32 v181, v138, v26
	v_dot4c_i32_i8_e32 v181, v139, v27
	v_dot4c_i32_i8_e32 v181, v140, v28
	v_dot4c_i32_i8_e32 v181, v141, v29
	v_dot4c_i32_i8_e32 v181, v142, v30
	v_dot4c_i32_i8_e32 v181, v143, v31
	s_nop 2
	v_add_u32_dpp v176, v176, v176 quad_perm:[1,0,3,2] row_mask:0xf bank_mask:0xf bound_ctrl:1
	v_add_u32_dpp v177, v177, v177 quad_perm:[1,0,3,2] row_mask:0xf bank_mask:0xf bound_ctrl:1
	v_add_u32_dpp v178, v178, v178 quad_perm:[1,0,3,2] row_mask:0xf bank_mask:0xf bound_ctrl:1
	v_add_u32_dpp v179, v179, v179 quad_perm:[1,0,3,2] row_mask:0xf bank_mask:0xf bound_ctrl:1
	v_add_u32_dpp v180, v180, v180 quad_perm:[1,0,3,2] row_mask:0xf bank_mask:0xf bound_ctrl:1
	v_add_u32_dpp v181, v181, v181 quad_perm:[1,0,3,2] row_mask:0xf bank_mask:0xf bound_ctrl:1
	v_add_u32_dpp v176, v176, v176 quad_perm:[2,3,0,1] row_mask:0xf bank_mask:0xf bound_ctrl:1
	v_add_u32_dpp v177, v177, v177 quad_perm:[2,3,0,1] row_mask:0xf bank_mask:0xf bound_ctrl:1
	v_add_u32_dpp v178, v178, v178 quad_perm:[2,3,0,1] row_mask:0xf bank_mask:0xf bound_ctrl:1
	v_add_u32_dpp v179, v179, v179 quad_perm:[2,3,0,1] row_mask:0xf bank_mask:0xf bound_ctrl:1
	v_add_u32_dpp v180, v180, v180 quad_perm:[2,3,0,1] row_mask:0xf bank_mask:0xf bound_ctrl:1
	v_add_u32_dpp v181, v181, v181 quad_perm:[2,3,0,1] row_mask:0xf bank_mask:0xf bound_ctrl:1
	v_add_u32_dpp v176, v176, v176 row_half_mirror row_mask:0xf bank_mask:0xf bound_ctrl:1
	v_add_u32_dpp v177, v177, v177 row_half_mirror row_mask:0xf bank_mask:0xf bound_ctrl:1
	v_add_u32_dpp v178, v178, v178 row_half_mirror row_mask:0xf bank_mask:0xf bound_ctrl:1
	v_add_u32_dpp v179, v179, v179 row_half_mirror row_mask:0xf bank_mask:0xf bound_ctrl:1
	v_add_u32_dpp v180, v180, v180 row_half_mirror row_mask:0xf bank_mask:0xf bound_ctrl:1
	v_add_u32_dpp v181, v181, v181 row_half_mirror row_mask:0xf bank_mask:0xf bound_ctrl:1
	v_add_u32_dpp v176, v176, v176 row_mirror row_mask:0xf bank_mask:0xf bound_ctrl:1
	v_add_u32_dpp v177, v177, v177 row_mirror row_mask:0xf bank_mask:0xf bound_ctrl:1
	v_add_u32_dpp v178, v178, v178 row_mirror row_mask:0xf bank_mask:0xf bound_ctrl:1
	v_add_u32_dpp v179, v179, v179 row_mirror row_mask:0xf bank_mask:0xf bound_ctrl:1
	v_add_u32_dpp v180, v180, v180 row_mirror row_mask:0xf bank_mask:0xf bound_ctrl:1
	v_add_u32_dpp v181, v181, v181 row_mirror row_mask:0xf bank_mask:0xf bound_ctrl:1
	v_cndmask_b32_e64 v152, v176, v177, s[82:83]
	v_cndmask_b32_e64 v152, v152, v178, s[84:85]
	v_cndmask_b32_e64 v152, v152, v179, s[86:87]
	v_cndmask_b32_e64 v152, v152, v180, s[88:89]
	v_cndmask_b32_e64 v152, v152, v181, s[90:91]
	s_waitcnt vmcnt(0)
	s_branch .Lp11a_gelu
; DI float gelu_t(float x) { float u = 0.7978845608028654f * (x + 0.044715f * x * x * x); float e = __expf(2.f * u); float t = 1.f - 2.f / (1.f + e); return 0.5f * x * (1.f + t); }
; DI void phase11a(const Params& P, char* smem_all) {
;     ...
;           d = dpp_row_sum_i(d);
;           const float dot = (float)d * (su[gi] * sx);
;           const float w = gl[gi] * gelu_t(dot) * sv[gi];
;           const int p = pl[gi];
;           if (l16 == 0 && p >= 0) W2[(long)t * 128 + (p & 7) * 16 + (p >> 3)] = w;
.Lp11a_l2:
	s_waitcnt vmcnt(6)
	v_mov_b32_e32 v176, 0
	v_dot4c_i32_i8_e32 v176, v48, v16
	v_dot4c_i32_i8_e32 v176, v49, v17
	v_dot4c_i32_i8_e32 v176, v50, v18
	v_dot4c_i32_i8_e32 v176, v51, v19
	v_dot4c_i32_i8_e32 v176, v52, v20
	v_dot4c_i32_i8_e32 v176, v53, v21
	v_dot4c_i32_i8_e32 v176, v54, v22
	v_dot4c_i32_i8_e32 v176, v55, v23
	v_dot4c_i32_i8_e32 v176, v56, v24
	v_dot4c_i32_i8_e32 v176, v57, v25
	v_dot4c_i32_i8_e32 v176, v58, v26
	v_dot4c_i32_i8_e32 v176, v59, v27
	v_dot4c_i32_i8_e32 v176, v60, v28
	v_dot4c_i32_i8_e32 v176, v61, v29
	v_dot4c_i32_i8_e32 v176, v62, v30
	v_dot4c_i32_i8_e32 v176, v63, v31
	s_waitcnt vmcnt(2)
	v_mov_b32_e32 v177, 0
	v_dot4c_i32_i8_e32 v177, v64, v16
	v_dot4c_i32_i8_e32 v177, v65, v17
	v_dot4c_i32_i8_e32 v177, v66, v18
	v_dot4c_i32_i8_e32 v177, v67, v19
	v_dot4c_i32_i8_e32 v177, v68, v20
	v_dot4c_i32_i8_e32 v177, v69, v21
	v_dot4c_i32_i8_e32 v177, v70, v22
	v_dot4c_i32_i8_e32 v177, v71, v23
	v_dot4c_i32_i8_e32 v177, v72, v24
	v_dot4c_i32_i8_e32 v177, v73, v25
	v_dot4c_i32_i8_e32 v177, v74, v26
	v_dot4c_i32_i8_e32 v177, v75, v27
	v_dot4c_i32_i8_e32 v177, v76, v28
	v_dot4c_i32_i8_e32 v177, v77, v29
	v_dot4c_i32_i8_e32 v177, v78, v30
	v_dot4c_i32_i8_e32 v177, v79, v31
	s_nop 2
	v_add_u32_dpp v176, v176, v176 quad_perm:[1,0,3,2] row_mask:0xf bank_mask:0xf bound_ctrl:1
	v_add_u32_dpp v177, v177, v177 quad_perm:[1,0,3,2] row_mask:0xf bank_mask:0xf bound_ctrl:1
	s_nop 0
	v_add_u32_dpp v176, v176, v176 quad_perm:[2,3,0,1] row_mask:0xf bank_mask:0xf bound_ctrl:1
	v_add_u32_dpp v177, v177, v177 quad_perm:[2,3,0,1] row_mask:0xf bank_mask:0xf bound_ctrl:1
	s_nop 0
	v_add_u32_dpp v176, v176, v176 row_half_mirror row_mask:0xf bank_mask:0xf bound_ctrl:1
	v_add_u32_dpp v177, v177, v177 row_half_mirror row_mask:0xf bank_mask:0xf bound_ctrl:1
	s_nop 0
	v_add_u32_dpp v176, v176, v176 row_mirror row_mask:0xf bank_mask:0xf bound_ctrl:1
	v_add_u32_dpp v177, v177, v177 row_mirror row_mask:0xf bank_mask:0xf bound_ctrl:1
	s_nop 0
	v_cndmask_b32_e64 v152, v176, v177, s[82:83]
	s_waitcnt vmcnt(0)
	s_branch .Lp11a_gelu
.Lp11a_gelu:
	v_cvt_f32_i32_e32 v182, v152
	v_mul_f32_e32 v183, s14, v156
	v_mul_f32_e32 v182, v183, v182
	v_mul_f32_e32 v183, 0x3d372713, v182
	v_mul_f32_e32 v183, v182, v183
	v_mul_f32_e32 v184, 0.5, v182
	v_fmac_f32_e32 v182, v182, v183
	v_mul_f32_e32 v182, 0x3f4c422a, v182
	v_add_f32_e32 v182, v182, v182
	v_mul_f32_e32 v182, 0x3fb8aa3b, v182
	v_exp_f32_e32 v182, v182
	v_and_b32_e32 v190, 0x7f, v154
	v_add_f32_e32 v182, 1.0, v182
	v_div_scale_f32 v185, s[0:1], v182, v182, 2.0
	v_rcp_f32_e32 v186, v185
	v_div_scale_f32 v187, vcc, 2.0, v182, 2.0
	v_fma_f32 v188, -v185, v186, 1.0
	v_fmac_f32_e32 v186, v188, v186
	v_mul_f32_e32 v188, v187, v186
	v_fma_f32 v189, -v185, v188, v187
	v_fmac_f32_e32 v188, v189, v186
	v_fma_f32 v187, -v185, v188, v187
	v_div_fmas_f32 v187, v187, v186, v188
	v_div_fixup_f32 v182, v187, v182, 2.0
	v_lshlrev_b32_e32 v191, 6, v190
	v_and_b32_e32 v191, 0x1c0, v191
	v_lshrrev_b32_e32 v190, 1, v190
	v_and_b32_e32 v190, 0x3c, v190
	v_or_b32_e32 v191, v191, v190
	v_sub_f32_e32 v182, 1.0, v182
	v_add_f32_e32 v182, 1.0, v182
	v_mul_f32_e32 v182, v184, v182
	v_mul_f32_e32 v182, v155, v182
	v_mul_f32_e32 v182, v153, v182
	s_cmp_lg_u32 s12, 0
	s_cbranch_scc1 .Lp11a_store_now
	v_mov_b32_e32 v192, v191
	v_mov_b32_e32 v193, v182
	s_mov_b64 s[72:73], s[16:17]
	s_mov_b64 s[74:75], s[36:37]
	s_mov_b32 s23, 1
	s_branch .Lp11a_chunk_end
